# pre-MLP rmsnorm fused: out-proj residual epilogue also writes bf16(x*gain) and per-row sum-of-squares partials; the norm phase only turns partials into 1/rms; the row scale is applied in f32 in the ML
# speedup vs baseline: 1.0014x; 1.0014x over previous
.LBB0_893:
	v_lshl_or_b32 v158, s26, 8, v164
	v_lshl_add_u32 v241, s27, 8, v162
	v_lshlrev_b32_e32 v240, 12, v241
	v_lshl_add_u32 v240, v158, 2, v240
	s_load_dwordx2 s[98:99], s[56:57], 0xd8
	s_load_dwordx2 s[100:101], s[56:57], 0xb0
	v_readlane_b32 s16, v255, 10
	v_lshlrev_b32_e32 v241, 11, v241
	v_lshl_add_u32 v241, v158, 1, v241
	s_lshl_b32 s16, s16, 10
	v_add_u32_e32 v166, s16, v158
	v_lshlrev_b32_e32 v166, 2, v166
	s_waitcnt lgkmcnt(0)
	global_load_dwordx4 v[232:235], v166, s[100:101]
	global_load_dwordx4 v[236:239], v166, s[100:101] offset:16
	global_load_dwordx4 v[150:153], v166, s[100:101] offset:512
	global_load_dwordx4 v[154:157], v166, s[100:101] offset:528
	v_readfirstlane_b32 s100, v2
	v_readfirstlane_b32 s101, v3
	s_add_u32 s98, s98, 0x2b89000
	s_addc_u32 s99, s99, 0
	s_nop 4
	v_mov_b32_e32 v158, v240
	global_load_dwordx4 v[166:169], v158, s[100:101]
	global_load_dwordx4 v[170:173], v158, s[100:101] offset:16
	global_load_dwordx4 v[174:177], v158, s[100:101] offset:512
	global_load_dwordx4 v[178:181], v158, s[100:101] offset:528
	v_add_u32_e32 v158, 0x10000, v158
	global_load_dwordx4 v[182:185], v158, s[100:101]
	global_load_dwordx4 v[186:189], v158, s[100:101] offset:16
	global_load_dwordx4 v[190:193], v158, s[100:101] offset:512
	global_load_dwordx4 v[194:197], v158, s[100:101] offset:528
	v_add_u32_e32 v158, 0x10000, v158
	global_load_dwordx4 v[200:203], v158, s[100:101]
	global_load_dwordx4 v[204:207], v158, s[100:101] offset:16
	global_load_dwordx4 v[208:211], v158, s[100:101] offset:512
	global_load_dwordx4 v[212:215], v158, s[100:101] offset:528
	v_add_u32_e32 v158, 0x10000, v158
	global_load_dwordx4 v[216:219], v158, s[100:101]
	global_load_dwordx4 v[220:223], v158, s[100:101] offset:16
	global_load_dwordx4 v[224:227], v158, s[100:101] offset:512
	global_load_dwordx4 v[228:231], v158, s[100:101] offset:528
	s_waitcnt vmcnt(0)
	v_pk_add_f32 v[128:129], v[128:129], v[166:167]
	v_pk_add_f32 v[130:131], v[130:131], v[168:169]
	v_pk_add_f32 v[124:125], v[124:125], v[170:171]
	v_pk_add_f32 v[126:127], v[126:127], v[172:173]
	v_pk_add_f32 v[112:113], v[112:113], v[174:175]
	v_pk_add_f32 v[114:115], v[114:115], v[176:177]
	v_pk_add_f32 v[104:105], v[104:105], v[178:179]
	v_pk_add_f32 v[106:107], v[106:107], v[180:181]
	v_pk_add_f32 v[120:121], v[120:121], v[182:183]
	v_pk_add_f32 v[122:123], v[122:123], v[184:185]
	v_pk_add_f32 v[116:117], v[116:117], v[186:187]
	v_pk_add_f32 v[118:119], v[118:119], v[188:189]
	v_pk_add_f32 v[96:97], v[96:97], v[190:191]
	v_pk_add_f32 v[98:99], v[98:99], v[192:193]
	v_pk_add_f32 v[88:89], v[88:89], v[194:195]
	v_pk_add_f32 v[90:91], v[90:91], v[196:197]
	v_pk_add_f32 v[108:109], v[108:109], v[200:201]
	v_pk_add_f32 v[110:111], v[110:111], v[202:203]
	v_pk_add_f32 v[100:101], v[100:101], v[204:205]
	v_pk_add_f32 v[102:103], v[102:103], v[206:207]
	v_pk_add_f32 v[80:81], v[80:81], v[208:209]
	v_pk_add_f32 v[82:83], v[82:83], v[210:211]
	v_pk_add_f32 v[76:77], v[76:77], v[212:213]
	v_pk_add_f32 v[78:79], v[78:79], v[214:215]
	v_pk_add_f32 v[92:93], v[92:93], v[216:217]
	v_pk_add_f32 v[94:95], v[94:95], v[218:219]
	v_pk_add_f32 v[84:85], v[84:85], v[220:221]
	v_pk_add_f32 v[86:87], v[86:87], v[222:223]
	v_pk_add_f32 v[72:73], v[72:73], v[224:225]
	v_pk_add_f32 v[74:75], v[74:75], v[226:227]
	v_pk_add_f32 v[68:69], v[68:69], v[228:229]
	v_pk_add_f32 v[70:71], v[70:71], v[230:231]
	v_mov_b32_e32 v158, v240
	global_store_dwordx4 v158, v[128:131], s[100:101]
	global_store_dwordx4 v158, v[124:127], s[100:101] offset:16
	global_store_dwordx4 v158, v[112:115], s[100:101] offset:512
	global_store_dwordx4 v158, v[104:107], s[100:101] offset:528
	v_add_u32_e32 v158, 0x10000, v158
	global_store_dwordx4 v158, v[120:123], s[100:101]
	global_store_dwordx4 v158, v[116:119], s[100:101] offset:16
	global_store_dwordx4 v158, v[96:99], s[100:101] offset:512
	global_store_dwordx4 v158, v[88:91], s[100:101] offset:528
	v_add_u32_e32 v158, 0x10000, v158
	global_store_dwordx4 v158, v[108:111], s[100:101]
	global_store_dwordx4 v158, v[100:103], s[100:101] offset:16
	global_store_dwordx4 v158, v[80:83], s[100:101] offset:512
	global_store_dwordx4 v158, v[76:79], s[100:101] offset:528
	v_add_u32_e32 v158, 0x10000, v158
	global_store_dwordx4 v158, v[92:95], s[100:101]
	global_store_dwordx4 v158, v[84:87], s[100:101] offset:16
	global_store_dwordx4 v158, v[72:75], s[100:101] offset:512
	global_store_dwordx4 v158, v[68:71], s[100:101] offset:528
	s_nop 1
	v_mov_b32_e32 v166, v241
	v_mul_f32_e32 v158, v128, v128
	v_fma_f32 v158, v129, v129, v158
	v_fma_f32 v158, v130, v130, v158
	v_fma_f32 v158, v131, v131, v158
	v_fma_f32 v158, v124, v124, v158
	v_fma_f32 v158, v125, v125, v158
	v_fma_f32 v158, v126, v126, v158
	v_fma_f32 v158, v127, v127, v158
	v_mul_f32_e32 v128, v128, v232
	v_mul_f32_e32 v129, v129, v233
	v_mul_f32_e32 v130, v130, v234
	v_mul_f32_e32 v131, v131, v235
	v_mul_f32_e32 v124, v124, v236
	v_mul_f32_e32 v125, v125, v237
	v_mul_f32_e32 v126, v126, v238
	v_mul_f32_e32 v127, v127, v239
	v_cvt_pk_bf16_f32 v128, v128, v129
	v_cvt_pk_bf16_f32 v129, v130, v131
	v_cvt_pk_bf16_f32 v130, v124, v125
	v_cvt_pk_bf16_f32 v131, v126, v127
	global_store_dwordx4 v166, v[128:131], s[98:99]
	v_fma_f32 v158, v112, v112, v158
	v_fma_f32 v158, v113, v113, v158
	v_fma_f32 v158, v114, v114, v158
	v_fma_f32 v158, v115, v115, v158
	v_fma_f32 v158, v104, v104, v158
	v_fma_f32 v158, v105, v105, v158
	v_fma_f32 v158, v106, v106, v158
	v_fma_f32 v158, v107, v107, v158
	v_mul_f32_e32 v112, v112, v150
	v_mul_f32_e32 v113, v113, v151
	v_mul_f32_e32 v114, v114, v152
	v_mul_f32_e32 v115, v115, v153
	v_mul_f32_e32 v104, v104, v154
	v_mul_f32_e32 v105, v105, v155
	v_mul_f32_e32 v106, v106, v156
	v_mul_f32_e32 v107, v107, v157
	v_cvt_pk_bf16_f32 v112, v112, v113
	v_cvt_pk_bf16_f32 v113, v114, v115
	v_cvt_pk_bf16_f32 v114, v104, v105
	v_cvt_pk_bf16_f32 v115, v106, v107
	global_store_dwordx4 v166, v[112:115], s[98:99] offset:256
	v_add_u32_e32 v166, 0x8000, v166
	v_mul_f32_e32 v159, v120, v120
	v_fma_f32 v159, v121, v121, v159
	v_fma_f32 v159, v122, v122, v159
	v_fma_f32 v159, v123, v123, v159
	v_fma_f32 v159, v116, v116, v159
	v_fma_f32 v159, v117, v117, v159
	v_fma_f32 v159, v118, v118, v159
	v_fma_f32 v159, v119, v119, v159
	v_mul_f32_e32 v120, v120, v232
	v_mul_f32_e32 v121, v121, v233
	v_mul_f32_e32 v122, v122, v234
	v_mul_f32_e32 v123, v123, v235
	v_mul_f32_e32 v116, v116, v236
	v_mul_f32_e32 v117, v117, v237
	v_mul_f32_e32 v118, v118, v238
	v_mul_f32_e32 v119, v119, v239
	v_cvt_pk_bf16_f32 v120, v120, v121
	v_cvt_pk_bf16_f32 v121, v122, v123
	v_cvt_pk_bf16_f32 v122, v116, v117
	v_cvt_pk_bf16_f32 v123, v118, v119
	global_store_dwordx4 v166, v[120:123], s[98:99]
	v_fma_f32 v159, v96, v96, v159
	v_fma_f32 v159, v97, v97, v159
	v_fma_f32 v159, v98, v98, v159
	v_fma_f32 v159, v99, v99, v159
	v_fma_f32 v159, v88, v88, v159
	v_fma_f32 v159, v89, v89, v159
	v_fma_f32 v159, v90, v90, v159
	v_fma_f32 v159, v91, v91, v159
	v_mul_f32_e32 v96, v96, v150
	v_mul_f32_e32 v97, v97, v151
	v_mul_f32_e32 v98, v98, v152
	v_mul_f32_e32 v99, v99, v153
	v_mul_f32_e32 v88, v88, v154
	v_mul_f32_e32 v89, v89, v155
	v_mul_f32_e32 v90, v90, v156
	v_mul_f32_e32 v91, v91, v157
	v_cvt_pk_bf16_f32 v96, v96, v97
	v_cvt_pk_bf16_f32 v97, v98, v99
	v_cvt_pk_bf16_f32 v98, v88, v89
	v_cvt_pk_bf16_f32 v99, v90, v91
	global_store_dwordx4 v166, v[96:99], s[98:99] offset:256
	v_add_u32_e32 v166, 0x8000, v166
	v_mul_f32_e32 v160, v108, v108
	v_fma_f32 v160, v109, v109, v160
	v_fma_f32 v160, v110, v110, v160
	v_fma_f32 v160, v111, v111, v160
	v_fma_f32 v160, v100, v100, v160
	v_fma_f32 v160, v101, v101, v160
	v_fma_f32 v160, v102, v102, v160
	v_fma_f32 v160, v103, v103, v160
	v_mul_f32_e32 v108, v108, v232
	v_mul_f32_e32 v109, v109, v233
	v_mul_f32_e32 v110, v110, v234
	v_mul_f32_e32 v111, v111, v235
	v_mul_f32_e32 v100, v100, v236
	v_mul_f32_e32 v101, v101, v237
	v_mul_f32_e32 v102, v102, v238
	v_mul_f32_e32 v103, v103, v239
	v_cvt_pk_bf16_f32 v108, v108, v109
	v_cvt_pk_bf16_f32 v109, v110, v111
	v_cvt_pk_bf16_f32 v110, v100, v101
	v_cvt_pk_bf16_f32 v111, v102, v103
	global_store_dwordx4 v166, v[108:111], s[98:99]
	v_fma_f32 v160, v80, v80, v160
	v_fma_f32 v160, v81, v81, v160
	v_fma_f32 v160, v82, v82, v160
	v_fma_f32 v160, v83, v83, v160
	v_fma_f32 v160, v76, v76, v160
	v_fma_f32 v160, v77, v77, v160
	v_fma_f32 v160, v78, v78, v160
	v_fma_f32 v160, v79, v79, v160
	v_mul_f32_e32 v80, v80, v150
	v_mul_f32_e32 v81, v81, v151
	v_mul_f32_e32 v82, v82, v152
	v_mul_f32_e32 v83, v83, v153
	v_mul_f32_e32 v76, v76, v154
	v_mul_f32_e32 v77, v77, v155
	v_mul_f32_e32 v78, v78, v156
	v_mul_f32_e32 v79, v79, v157
	v_cvt_pk_bf16_f32 v80, v80, v81
	v_cvt_pk_bf16_f32 v81, v82, v83
	v_cvt_pk_bf16_f32 v82, v76, v77
	v_cvt_pk_bf16_f32 v83, v78, v79
	global_store_dwordx4 v166, v[80:83], s[98:99] offset:256
	v_add_u32_e32 v166, 0x8000, v166
	v_mul_f32_e32 v161, v92, v92
	v_fma_f32 v161, v93, v93, v161
	v_fma_f32 v161, v94, v94, v161
	v_fma_f32 v161, v95, v95, v161
	v_fma_f32 v161, v84, v84, v161
	v_fma_f32 v161, v85, v85, v161
	v_fma_f32 v161, v86, v86, v161
	v_fma_f32 v161, v87, v87, v161
	v_mul_f32_e32 v92, v92, v232
	v_mul_f32_e32 v93, v93, v233
	v_mul_f32_e32 v94, v94, v234
	v_mul_f32_e32 v95, v95, v235
	v_mul_f32_e32 v84, v84, v236
	v_mul_f32_e32 v85, v85, v237
	v_mul_f32_e32 v86, v86, v238
	v_mul_f32_e32 v87, v87, v239
	v_cvt_pk_bf16_f32 v92, v92, v93
	v_cvt_pk_bf16_f32 v93, v94, v95
	v_cvt_pk_bf16_f32 v94, v84, v85
	v_cvt_pk_bf16_f32 v95, v86, v87
	global_store_dwordx4 v166, v[92:95], s[98:99]
	v_fma_f32 v161, v72, v72, v161
	v_fma_f32 v161, v73, v73, v161
	v_fma_f32 v161, v74, v74, v161
	v_fma_f32 v161, v75, v75, v161
	v_fma_f32 v161, v68, v68, v161
	v_fma_f32 v161, v69, v69, v161
	v_fma_f32 v161, v70, v70, v161
	v_fma_f32 v161, v71, v71, v161
	v_mul_f32_e32 v72, v72, v150
	v_mul_f32_e32 v73, v73, v151
	v_mul_f32_e32 v74, v74, v152
	v_mul_f32_e32 v75, v75, v153
	v_mul_f32_e32 v68, v68, v154
	v_mul_f32_e32 v69, v69, v155
	v_mul_f32_e32 v70, v70, v156
	v_mul_f32_e32 v71, v71, v157
	v_cvt_pk_bf16_f32 v72, v72, v73
	v_cvt_pk_bf16_f32 v73, v74, v75
	v_cvt_pk_bf16_f32 v74, v68, v69
	v_cvt_pk_bf16_f32 v75, v70, v71
	global_store_dwordx4 v166, v[72:75], s[98:99] offset:256
	v_mbcnt_lo_u32_b32 v167, -1, 0
	v_mbcnt_hi_u32_b32 v167, -1, v167
	v_xor_b32_e32 v168, 16, v167
	v_lshlrev_b32_e32 v168, 2, v168
	v_xor_b32_e32 v169, 32, v167
	v_lshlrev_b32_e32 v169, 2, v169
	ds_bpermute_b32 v170, v168, v158
	s_waitcnt lgkmcnt(0)
	v_add_f32_e32 v158, v158, v170
	ds_bpermute_b32 v170, v169, v158
	s_waitcnt lgkmcnt(0)
	v_add_f32_e32 v158, v158, v170
	ds_bpermute_b32 v170, v168, v159
	s_waitcnt lgkmcnt(0)
	v_add_f32_e32 v159, v159, v170
	ds_bpermute_b32 v170, v169, v159
	s_waitcnt lgkmcnt(0)
	v_add_f32_e32 v159, v159, v170
	ds_bpermute_b32 v170, v168, v160
	s_waitcnt lgkmcnt(0)
	v_add_f32_e32 v160, v160, v170
	ds_bpermute_b32 v170, v169, v160
	s_waitcnt lgkmcnt(0)
	v_add_f32_e32 v160, v160, v170
	ds_bpermute_b32 v170, v168, v161
	s_waitcnt lgkmcnt(0)
	v_add_f32_e32 v161, v161, v170
	ds_bpermute_b32 v170, v169, v161
	s_waitcnt lgkmcnt(0)
	v_add_f32_e32 v161, v161, v170
	v_lshrrev_b32_e32 v171, 12, v240
	v_lshlrev_b32_e32 v171, 6, v171
	v_lshrrev_b32_e32 v172, 5, v164
	v_lshl_add_u32 v172, s26, 2, v172
	v_lshl_add_u32 v171, v172, 2, v171
	v_add_u32_e32 v171, 0x5c00000, v171
	s_mov_b64 exec, 0xffff
	global_store_dword v171, v158, s[98:99]
	global_store_dword v171, v159, s[98:99] offset:1024
	global_store_dword v171, v160, s[98:99] offset:2048
	global_store_dword v171, v161, s[98:99] offset:3072
	s_mov_b64 exec, -1
	v_add_u32_e32 v158, 0x80000, v240
	global_load_dwordx4 v[166:169], v158, s[100:101]
	global_load_dwordx4 v[170:173], v158, s[100:101] offset:16
	global_load_dwordx4 v[174:177], v158, s[100:101] offset:512
	global_load_dwordx4 v[178:181], v158, s[100:101] offset:528
	v_add_u32_e32 v158, 0x10000, v158
	global_load_dwordx4 v[182:185], v158, s[100:101]
	global_load_dwordx4 v[186:189], v158, s[100:101] offset:16
	global_load_dwordx4 v[190:193], v158, s[100:101] offset:512
	global_load_dwordx4 v[194:197], v158, s[100:101] offset:528
	v_add_u32_e32 v158, 0x10000, v158
	global_load_dwordx4 v[200:203], v158, s[100:101]
	global_load_dwordx4 v[204:207], v158, s[100:101] offset:16
	global_load_dwordx4 v[208:211], v158, s[100:101] offset:512
	global_load_dwordx4 v[212:215], v158, s[100:101] offset:528
	v_add_u32_e32 v158, 0x10000, v158
	global_load_dwordx4 v[216:219], v158, s[100:101]
	global_load_dwordx4 v[220:223], v158, s[100:101] offset:16
	global_load_dwordx4 v[224:227], v158, s[100:101] offset:512
	global_load_dwordx4 v[228:231], v158, s[100:101] offset:528
	s_waitcnt vmcnt(0)
	v_pk_add_f32 v[64:65], v[64:65], v[166:167]
	v_pk_add_f32 v[66:67], v[66:67], v[168:169]
	v_pk_add_f32 v[60:61], v[60:61], v[170:171]
	v_pk_add_f32 v[62:63], v[62:63], v[172:173]
	v_pk_add_f32 v[52:53], v[52:53], v[174:175]
	v_pk_add_f32 v[54:55], v[54:55], v[176:177]
	v_pk_add_f32 v[44:45], v[44:45], v[178:179]
	v_pk_add_f32 v[46:47], v[46:47], v[180:181]
	v_pk_add_f32 v[56:57], v[56:57], v[182:183]
	v_pk_add_f32 v[58:59], v[58:59], v[184:185]
	v_pk_add_f32 v[48:49], v[48:49], v[186:187]
	v_pk_add_f32 v[50:51], v[50:51], v[188:189]
	v_pk_add_f32 v[36:37], v[36:37], v[190:191]
	v_pk_add_f32 v[38:39], v[38:39], v[192:193]
	v_pk_add_f32 v[28:29], v[28:29], v[194:195]
	v_pk_add_f32 v[30:31], v[30:31], v[196:197]
	v_pk_add_f32 v[40:41], v[40:41], v[200:201]
	v_pk_add_f32 v[42:43], v[42:43], v[202:203]
	v_pk_add_f32 v[32:33], v[32:33], v[204:205]
	v_pk_add_f32 v[34:35], v[34:35], v[206:207]
	v_pk_add_f32 v[20:21], v[20:21], v[208:209]
	v_pk_add_f32 v[22:23], v[22:23], v[210:211]
	v_pk_add_f32 v[12:13], v[12:13], v[212:213]
	v_pk_add_f32 v[14:15], v[14:15], v[214:215]
	v_pk_add_f32 v[24:25], v[24:25], v[216:217]
	v_pk_add_f32 v[26:27], v[26:27], v[218:219]
	v_pk_add_f32 v[16:17], v[16:17], v[220:221]
	v_pk_add_f32 v[18:19], v[18:19], v[222:223]
	v_pk_add_f32 v[8:9], v[8:9], v[224:225]
	v_pk_add_f32 v[10:11], v[10:11], v[226:227]
	v_pk_add_f32 v[4:5], v[4:5], v[228:229]
	v_pk_add_f32 v[6:7], v[6:7], v[230:231]
	v_add_u32_e32 v158, 0x80000, v240
	global_store_dwordx4 v158, v[64:67], s[100:101]
	global_store_dwordx4 v158, v[60:63], s[100:101] offset:16
	global_store_dwordx4 v158, v[52:55], s[100:101] offset:512
	global_store_dwordx4 v158, v[44:47], s[100:101] offset:528
	v_add_u32_e32 v158, 0x10000, v158
	global_store_dwordx4 v158, v[56:59], s[100:101]
	global_store_dwordx4 v158, v[48:51], s[100:101] offset:16
	global_store_dwordx4 v158, v[36:39], s[100:101] offset:512
	global_store_dwordx4 v158, v[28:31], s[100:101] offset:528
	v_add_u32_e32 v158, 0x10000, v158
	global_store_dwordx4 v158, v[40:43], s[100:101]
	global_store_dwordx4 v158, v[32:35], s[100:101] offset:16
	global_store_dwordx4 v158, v[20:23], s[100:101] offset:512
	global_store_dwordx4 v158, v[12:15], s[100:101] offset:528
	v_add_u32_e32 v158, 0x10000, v158
	global_store_dwordx4 v158, v[24:27], s[100:101]
	global_store_dwordx4 v158, v[16:19], s[100:101] offset:16
	global_store_dwordx4 v158, v[8:11], s[100:101] offset:512
	global_store_dwordx4 v158, v[4:7], s[100:101] offset:528
	s_nop 1
	v_add_u32_e32 v166, 0x40000, v241
	v_mul_f32_e32 v158, v64, v64
	v_fma_f32 v158, v65, v65, v158
	v_fma_f32 v158, v66, v66, v158
	v_fma_f32 v158, v67, v67, v158
	v_fma_f32 v158, v60, v60, v158
	v_fma_f32 v158, v61, v61, v158
	v_fma_f32 v158, v62, v62, v158
	v_fma_f32 v158, v63, v63, v158
	v_mul_f32_e32 v64, v64, v232
	v_mul_f32_e32 v65, v65, v233
	v_mul_f32_e32 v66, v66, v234
	v_mul_f32_e32 v67, v67, v235
	v_mul_f32_e32 v60, v60, v236
	v_mul_f32_e32 v61, v61, v237
	v_mul_f32_e32 v62, v62, v238
	v_mul_f32_e32 v63, v63, v239
	v_cvt_pk_bf16_f32 v64, v64, v65
	v_cvt_pk_bf16_f32 v65, v66, v67
	v_cvt_pk_bf16_f32 v66, v60, v61
	v_cvt_pk_bf16_f32 v67, v62, v63
	global_store_dwordx4 v166, v[64:67], s[98:99]
	v_fma_f32 v158, v52, v52, v158
	v_fma_f32 v158, v53, v53, v158
	v_fma_f32 v158, v54, v54, v158
	v_fma_f32 v158, v55, v55, v158
	v_fma_f32 v158, v44, v44, v158
	v_fma_f32 v158, v45, v45, v158
	v_fma_f32 v158, v46, v46, v158
	v_fma_f32 v158, v47, v47, v158
	v_mul_f32_e32 v52, v52, v150
	v_mul_f32_e32 v53, v53, v151
	v_mul_f32_e32 v54, v54, v152
	v_mul_f32_e32 v55, v55, v153
	v_mul_f32_e32 v44, v44, v154
	v_mul_f32_e32 v45, v45, v155
	v_mul_f32_e32 v46, v46, v156
	v_mul_f32_e32 v47, v47, v157
	v_cvt_pk_bf16_f32 v52, v52, v53
	v_cvt_pk_bf16_f32 v53, v54, v55
	v_cvt_pk_bf16_f32 v54, v44, v45
	v_cvt_pk_bf16_f32 v55, v46, v47
	global_store_dwordx4 v166, v[52:55], s[98:99] offset:256
	v_add_u32_e32 v166, 0x8000, v166
	v_mul_f32_e32 v159, v56, v56
	v_fma_f32 v159, v57, v57, v159
	v_fma_f32 v159, v58, v58, v159
	v_fma_f32 v159, v59, v59, v159
	v_fma_f32 v159, v48, v48, v159
	v_fma_f32 v159, v49, v49, v159
	v_fma_f32 v159, v50, v50, v159
	v_fma_f32 v159, v51, v51, v159
	v_mul_f32_e32 v56, v56, v232
	v_mul_f32_e32 v57, v57, v233
	v_mul_f32_e32 v58, v58, v234
	v_mul_f32_e32 v59, v59, v235
	v_mul_f32_e32 v48, v48, v236
	v_mul_f32_e32 v49, v49, v237
	v_mul_f32_e32 v50, v50, v238
	v_mul_f32_e32 v51, v51, v239
	v_cvt_pk_bf16_f32 v56, v56, v57
	v_cvt_pk_bf16_f32 v57, v58, v59
	v_cvt_pk_bf16_f32 v58, v48, v49
	v_cvt_pk_bf16_f32 v59, v50, v51
	global_store_dwordx4 v166, v[56:59], s[98:99]
	v_fma_f32 v159, v36, v36, v159
	v_fma_f32 v159, v37, v37, v159
	v_fma_f32 v159, v38, v38, v159
	v_fma_f32 v159, v39, v39, v159
	v_fma_f32 v159, v28, v28, v159
	v_fma_f32 v159, v29, v29, v159
	v_fma_f32 v159, v30, v30, v159
	v_fma_f32 v159, v31, v31, v159
	v_mul_f32_e32 v36, v36, v150
	v_mul_f32_e32 v37, v37, v151
	v_mul_f32_e32 v38, v38, v152
	v_mul_f32_e32 v39, v39, v153
	v_mul_f32_e32 v28, v28, v154
	v_mul_f32_e32 v29, v29, v155
	v_mul_f32_e32 v30, v30, v156
	v_mul_f32_e32 v31, v31, v157
	v_cvt_pk_bf16_f32 v36, v36, v37
	v_cvt_pk_bf16_f32 v37, v38, v39
	v_cvt_pk_bf16_f32 v38, v28, v29
	v_cvt_pk_bf16_f32 v39, v30, v31
	global_store_dwordx4 v166, v[36:39], s[98:99] offset:256
	v_add_u32_e32 v166, 0x8000, v166
	v_mul_f32_e32 v160, v40, v40
	v_fma_f32 v160, v41, v41, v160
	v_fma_f32 v160, v42, v42, v160
	v_fma_f32 v160, v43, v43, v160
	v_fma_f32 v160, v32, v32, v160
	v_fma_f32 v160, v33, v33, v160
	v_fma_f32 v160, v34, v34, v160
	v_fma_f32 v160, v35, v35, v160
	v_mul_f32_e32 v40, v40, v232
	v_mul_f32_e32 v41, v41, v233
	v_mul_f32_e32 v42, v42, v234
	v_mul_f32_e32 v43, v43, v235
	v_mul_f32_e32 v32, v32, v236
	v_mul_f32_e32 v33, v33, v237
	v_mul_f32_e32 v34, v34, v238
	v_mul_f32_e32 v35, v35, v239
	v_cvt_pk_bf16_f32 v40, v40, v41
	v_cvt_pk_bf16_f32 v41, v42, v43
	v_cvt_pk_bf16_f32 v42, v32, v33
	v_cvt_pk_bf16_f32 v43, v34, v35
	global_store_dwordx4 v166, v[40:43], s[98:99]
	v_fma_f32 v160, v20, v20, v160
	v_fma_f32 v160, v21, v21, v160
	v_fma_f32 v160, v22, v22, v160
	v_fma_f32 v160, v23, v23, v160
	v_fma_f32 v160, v12, v12, v160
	v_fma_f32 v160, v13, v13, v160
	v_fma_f32 v160, v14, v14, v160
	v_fma_f32 v160, v15, v15, v160
	v_mul_f32_e32 v20, v20, v150
	v_mul_f32_e32 v21, v21, v151
	v_mul_f32_e32 v22, v22, v152
	v_mul_f32_e32 v23, v23, v153
	v_mul_f32_e32 v12, v12, v154
	v_mul_f32_e32 v13, v13, v155
	v_mul_f32_e32 v14, v14, v156
	v_mul_f32_e32 v15, v15, v157
	v_cvt_pk_bf16_f32 v20, v20, v21
	v_cvt_pk_bf16_f32 v21, v22, v23
	v_cvt_pk_bf16_f32 v22, v12, v13
	v_cvt_pk_bf16_f32 v23, v14, v15
	global_store_dwordx4 v166, v[20:23], s[98:99] offset:256
	v_add_u32_e32 v166, 0x8000, v166
	v_mul_f32_e32 v161, v24, v24
	v_fma_f32 v161, v25, v25, v161
	v_fma_f32 v161, v26, v26, v161
	v_fma_f32 v161, v27, v27, v161
	v_fma_f32 v161, v16, v16, v161
	v_fma_f32 v161, v17, v17, v161
	v_fma_f32 v161, v18, v18, v161
	v_fma_f32 v161, v19, v19, v161
	v_mul_f32_e32 v24, v24, v232
	v_mul_f32_e32 v25, v25, v233
	v_mul_f32_e32 v26, v26, v234
	v_mul_f32_e32 v27, v27, v235
	v_mul_f32_e32 v16, v16, v236
	v_mul_f32_e32 v17, v17, v237
	v_mul_f32_e32 v18, v18, v238
	v_mul_f32_e32 v19, v19, v239
	v_cvt_pk_bf16_f32 v24, v24, v25
	v_cvt_pk_bf16_f32 v25, v26, v27
	v_cvt_pk_bf16_f32 v26, v16, v17
	v_cvt_pk_bf16_f32 v27, v18, v19
	global_store_dwordx4 v166, v[24:27], s[98:99]
	v_fma_f32 v161, v8, v8, v161
	v_fma_f32 v161, v9, v9, v161
	v_fma_f32 v161, v10, v10, v161
	v_fma_f32 v161, v11, v11, v161
	v_fma_f32 v161, v4, v4, v161
	v_fma_f32 v161, v5, v5, v161
	v_fma_f32 v161, v6, v6, v161
	v_fma_f32 v161, v7, v7, v161
	v_mul_f32_e32 v8, v8, v150
	v_mul_f32_e32 v9, v9, v151
	v_mul_f32_e32 v10, v10, v152
	v_mul_f32_e32 v11, v11, v153
	v_mul_f32_e32 v4, v4, v154
	v_mul_f32_e32 v5, v5, v155
	v_mul_f32_e32 v6, v6, v156
	v_mul_f32_e32 v7, v7, v157
	v_cvt_pk_bf16_f32 v8, v8, v9
	v_cvt_pk_bf16_f32 v9, v10, v11
	v_cvt_pk_bf16_f32 v10, v4, v5
	v_cvt_pk_bf16_f32 v11, v6, v7
	global_store_dwordx4 v166, v[8:11], s[98:99] offset:256
	v_mbcnt_lo_u32_b32 v167, -1, 0
	v_mbcnt_hi_u32_b32 v167, -1, v167
	v_xor_b32_e32 v168, 16, v167
	v_lshlrev_b32_e32 v168, 2, v168
	v_xor_b32_e32 v169, 32, v167
	v_lshlrev_b32_e32 v169, 2, v169
	ds_bpermute_b32 v170, v168, v158
	s_waitcnt lgkmcnt(0)
	v_add_f32_e32 v158, v158, v170
	ds_bpermute_b32 v170, v169, v158
	s_waitcnt lgkmcnt(0)
	v_add_f32_e32 v158, v158, v170
	ds_bpermute_b32 v170, v168, v159
	s_waitcnt lgkmcnt(0)
	v_add_f32_e32 v159, v159, v170
	ds_bpermute_b32 v170, v169, v159
	s_waitcnt lgkmcnt(0)
	v_add_f32_e32 v159, v159, v170
	ds_bpermute_b32 v170, v168, v160
	s_waitcnt lgkmcnt(0)
	v_add_f32_e32 v160, v160, v170
	ds_bpermute_b32 v170, v169, v160
	s_waitcnt lgkmcnt(0)
	v_add_f32_e32 v160, v160, v170
	ds_bpermute_b32 v170, v168, v161
	s_waitcnt lgkmcnt(0)
	v_add_f32_e32 v161, v161, v170
	ds_bpermute_b32 v170, v169, v161
	s_waitcnt lgkmcnt(0)
	v_add_f32_e32 v161, v161, v170
	v_lshrrev_b32_e32 v171, 12, v240
	v_lshlrev_b32_e32 v171, 6, v171
	v_lshrrev_b32_e32 v172, 5, v164
	v_lshl_add_u32 v172, s26, 2, v172
	v_lshl_add_u32 v171, v172, 2, v171
	v_add_u32_e32 v171, 0x5c02000, v171
	s_mov_b64 exec, 0xffff
	global_store_dword v171, v158, s[98:99]
	global_store_dword v171, v159, s[98:99] offset:1024
	global_store_dword v171, v160, s[98:99] offset:2048
	global_store_dword v171, v161, s[98:99] offset:3072
	s_mov_b64 exec, -1
	s_mov_b64 s[16:17], -1
	s_andn2_b64 vcc, exec, s[4:5]
	s_cbranch_vccnz .LBB0_882
	s_andn2_b64 vcc, exec, s[6:7]
	s_cbranch_vccnz .LBB0_881
	s_barrier
	s_branch .LBB0_881

.LBB0_943:
	s_cmp_le_i32 s58, s40
	s_cselect_b64 s[0:1], -1, 0
	s_and_b64 s[4:5], s[0:1], s[44:45]
	s_andn2_b64 vcc, exec, s[4:5]
	s_cbranch_vccnz .LBB0_947
	s_mov_b32 s4, s80
	v_mbcnt_lo_u32_b32 v0, -1, 0
	v_mbcnt_hi_u32_b32 v0, -1, v0
	s_add_i32 s4, s4, s81
	s_mov_b64 s[6:7], s[56:57]
	s_cmpk_gt_i32 s4, 0x7fff
	s_cbranch_scc1 .LBB0_947
	s_waitcnt vmcnt(0) lgkmcnt(0)
	s_load_dwordx2 s[98:99], s[56:57], 0xd8
	v_lshrrev_b32_e32 v2, 4, v0
	v_and_b32_e32 v3, 15, v0
	v_lshlrev_b32_e32 v4, 11, v2
	v_add_u32_e32 v4, s4, v4
	v_lshlrev_b32_e32 v5, 6, v4
	v_lshl_add_u32 v5, v3, 2, v5
	v_lshlrev_b32_e32 v6, 2, v4
	s_waitcnt lgkmcnt(0)
	s_add_u32 s98, s98, 0x8789000
	s_addc_u32 s99, s99, 0
	global_load_dword v8, v5, s[98:99]
	v_add_u32_e32 v5, 0x80000, v5
	global_load_dword v9, v5, s[98:99]
	v_add_u32_e32 v5, 0x80000, v5
	global_load_dword v10, v5, s[98:99]
	v_add_u32_e32 v5, 0x80000, v5
	global_load_dword v11, v5, s[98:99]
	s_waitcnt vmcnt(0)
	v_lshlrev_b32_e32 v7, 2, v0
	v_xor_b32_e32 v12, 4, v7
	v_xor_b32_e32 v13, 8, v7
	v_xor_b32_e32 v14, 16, v7
	v_xor_b32_e32 v15, 32, v7
	ds_bpermute_b32 v16, v12, v8
	s_waitcnt lgkmcnt(0)
	v_add_f32_e32 v8, v8, v16
	ds_bpermute_b32 v16, v13, v8
	s_waitcnt lgkmcnt(0)
	v_add_f32_e32 v8, v8, v16
	ds_bpermute_b32 v16, v14, v8
	s_waitcnt lgkmcnt(0)
	v_add_f32_e32 v8, v8, v16
	ds_bpermute_b32 v16, v15, v8
	s_waitcnt lgkmcnt(0)
	v_add_f32_e32 v8, v8, v16
	ds_bpermute_b32 v16, v12, v9
	s_waitcnt lgkmcnt(0)
	v_add_f32_e32 v9, v9, v16
	ds_bpermute_b32 v16, v13, v9
	s_waitcnt lgkmcnt(0)
	v_add_f32_e32 v9, v9, v16
	ds_bpermute_b32 v16, v14, v9
	s_waitcnt lgkmcnt(0)
	v_add_f32_e32 v9, v9, v16
	ds_bpermute_b32 v16, v15, v9
	s_waitcnt lgkmcnt(0)
	v_add_f32_e32 v9, v9, v16
	ds_bpermute_b32 v16, v12, v10
	s_waitcnt lgkmcnt(0)
	v_add_f32_e32 v10, v10, v16
	ds_bpermute_b32 v16, v13, v10
	s_waitcnt lgkmcnt(0)
	v_add_f32_e32 v10, v10, v16
	ds_bpermute_b32 v16, v14, v10
	s_waitcnt lgkmcnt(0)
	v_add_f32_e32 v10, v10, v16
	ds_bpermute_b32 v16, v15, v10
	s_waitcnt lgkmcnt(0)
	v_add_f32_e32 v10, v10, v16
	ds_bpermute_b32 v16, v12, v11
	s_waitcnt lgkmcnt(0)
	v_add_f32_e32 v11, v11, v16
	ds_bpermute_b32 v16, v13, v11
	s_waitcnt lgkmcnt(0)
	v_add_f32_e32 v11, v11, v16
	ds_bpermute_b32 v16, v14, v11
	s_waitcnt lgkmcnt(0)
	v_add_f32_e32 v11, v11, v16
	ds_bpermute_b32 v16, v15, v11
	s_waitcnt lgkmcnt(0)
	v_add_f32_e32 v11, v11, v16
	v_mov_b32_e32 v17, 0x358637bd
	v_mov_b32_e32 v18, 0x800000
	s_mov_b32 s100, 0x10001
	s_mov_b32 s101, 0x10001
	v_fmamk_f32 v8, v8, 0x3a800000, v17
	v_cmp_gt_f32_e32 vcc, v18, v8
	v_mul_f32_e32 v16, 0x4b800000, v8
	s_nop 0
	v_cndmask_b32_e32 v8, v8, v16, vcc
	v_rsq_f32_e32 v8, v8
	s_nop 0
	v_mul_f32_e32 v16, 0x45800000, v8
	v_cndmask_b32_e32 v8, v8, v16, vcc
	v_fmamk_f32 v9, v9, 0x3a800000, v17
	v_cmp_gt_f32_e32 vcc, v18, v9
	v_mul_f32_e32 v16, 0x4b800000, v9
	s_nop 0
	v_cndmask_b32_e32 v9, v9, v16, vcc
	v_rsq_f32_e32 v9, v9
	s_nop 0
	v_mul_f32_e32 v16, 0x45800000, v9
	v_cndmask_b32_e32 v9, v9, v16, vcc
	v_fmamk_f32 v10, v10, 0x3a800000, v17
	v_cmp_gt_f32_e32 vcc, v18, v10
	v_mul_f32_e32 v16, 0x4b800000, v10
	s_nop 0
	v_cndmask_b32_e32 v10, v10, v16, vcc
	v_rsq_f32_e32 v10, v10
	s_nop 0
	v_mul_f32_e32 v16, 0x45800000, v10
	v_cndmask_b32_e32 v10, v10, v16, vcc
	v_fmamk_f32 v11, v11, 0x3a800000, v17
	v_cmp_gt_f32_e32 vcc, v18, v11
	v_mul_f32_e32 v16, 0x4b800000, v11
	s_nop 0
	v_cndmask_b32_e32 v11, v11, v16, vcc
	v_rsq_f32_e32 v11, v11
	s_nop 0
	v_mul_f32_e32 v16, 0x45800000, v11
	v_cndmask_b32_e32 v11, v11, v16, vcc
	s_mov_b64 exec, s[100:101]
	v_add_u32_e32 v6, 0x200000, v6
	global_store_dword v6, v8, s[98:99]
	v_add_u32_e32 v6, 0x8000, v6
	global_store_dword v6, v9, s[98:99]
	v_add_u32_e32 v6, 0x8000, v6
	global_store_dword v6, v10, s[98:99]
	v_add_u32_e32 v6, 0x8000, v6
	global_store_dword v6, v11, s[98:99]
	s_mov_b64 exec, -1

.LBB0_1010:
	s_load_dwordx2 s[98:99], s[56:57], 0xd8
	v_lshl_add_u32 v216, s27, 8, v158
	v_lshlrev_b32_e32 v216, 2, v216
	s_waitcnt lgkmcnt(0)
	s_add_u32 s98, s98, 0x8989000
	s_addc_u32 s99, s99, 0
	global_load_dword v200, v216, s[98:99]
	global_load_dword v202, v216, s[98:99] offset:64
	global_load_dword v204, v216, s[98:99] offset:128
	global_load_dword v206, v216, s[98:99] offset:192
	global_load_dword v208, v216, s[98:99] offset:512
	global_load_dword v210, v216, s[98:99] offset:576
	global_load_dword v212, v216, s[98:99] offset:640
	global_load_dword v214, v216, s[98:99] offset:704
	s_waitcnt vmcnt(0)
	v_pk_mul_f32 v[126:127], v[126:127], v[200:201] op_sel_hi:[1,0]
	v_pk_mul_f32 v[128:129], v[128:129], v[200:201] op_sel_hi:[1,0]
	v_pk_mul_f32 v[122:123], v[122:123], v[200:201] op_sel_hi:[1,0]
	v_pk_mul_f32 v[124:125], v[124:125], v[200:201] op_sel_hi:[1,0]
	v_pk_mul_f32 v[118:119], v[118:119], v[200:201] op_sel_hi:[1,0]
	v_pk_mul_f32 v[120:121], v[120:121], v[200:201] op_sel_hi:[1,0]
	v_pk_mul_f32 v[114:115], v[114:115], v[200:201] op_sel_hi:[1,0]
	v_pk_mul_f32 v[116:117], v[116:117], v[200:201] op_sel_hi:[1,0]
	v_pk_mul_f32 v[110:111], v[110:111], v[202:203] op_sel_hi:[1,0]
	v_pk_mul_f32 v[112:113], v[112:113], v[202:203] op_sel_hi:[1,0]
	v_pk_mul_f32 v[106:107], v[106:107], v[202:203] op_sel_hi:[1,0]
	v_pk_mul_f32 v[108:109], v[108:109], v[202:203] op_sel_hi:[1,0]
	v_pk_mul_f32 v[102:103], v[102:103], v[202:203] op_sel_hi:[1,0]
	v_pk_mul_f32 v[104:105], v[104:105], v[202:203] op_sel_hi:[1,0]
	v_pk_mul_f32 v[98:99], v[98:99], v[202:203] op_sel_hi:[1,0]
	v_pk_mul_f32 v[100:101], v[100:101], v[202:203] op_sel_hi:[1,0]
	v_pk_mul_f32 v[94:95], v[94:95], v[204:205] op_sel_hi:[1,0]
	v_pk_mul_f32 v[96:97], v[96:97], v[204:205] op_sel_hi:[1,0]
	v_pk_mul_f32 v[90:91], v[90:91], v[204:205] op_sel_hi:[1,0]
	v_pk_mul_f32 v[92:93], v[92:93], v[204:205] op_sel_hi:[1,0]
	v_pk_mul_f32 v[86:87], v[86:87], v[204:205] op_sel_hi:[1,0]
	v_pk_mul_f32 v[88:89], v[88:89], v[204:205] op_sel_hi:[1,0]
	v_pk_mul_f32 v[82:83], v[82:83], v[204:205] op_sel_hi:[1,0]
	v_pk_mul_f32 v[84:85], v[84:85], v[204:205] op_sel_hi:[1,0]
	v_pk_mul_f32 v[78:79], v[78:79], v[206:207] op_sel_hi:[1,0]
	v_pk_mul_f32 v[80:81], v[80:81], v[206:207] op_sel_hi:[1,0]
	v_pk_mul_f32 v[74:75], v[74:75], v[206:207] op_sel_hi:[1,0]
	v_pk_mul_f32 v[76:77], v[76:77], v[206:207] op_sel_hi:[1,0]
	v_pk_mul_f32 v[70:71], v[70:71], v[206:207] op_sel_hi:[1,0]
	v_pk_mul_f32 v[72:73], v[72:73], v[206:207] op_sel_hi:[1,0]
	v_pk_mul_f32 v[66:67], v[66:67], v[206:207] op_sel_hi:[1,0]
	v_pk_mul_f32 v[68:69], v[68:69], v[206:207] op_sel_hi:[1,0]
	v_pk_mul_f32 v[62:63], v[62:63], v[208:209] op_sel_hi:[1,0]
	v_pk_mul_f32 v[64:65], v[64:65], v[208:209] op_sel_hi:[1,0]
	v_pk_mul_f32 v[58:59], v[58:59], v[208:209] op_sel_hi:[1,0]
	v_pk_mul_f32 v[60:61], v[60:61], v[208:209] op_sel_hi:[1,0]
	v_pk_mul_f32 v[54:55], v[54:55], v[208:209] op_sel_hi:[1,0]
	v_pk_mul_f32 v[56:57], v[56:57], v[208:209] op_sel_hi:[1,0]
	v_pk_mul_f32 v[50:51], v[50:51], v[208:209] op_sel_hi:[1,0]
	v_pk_mul_f32 v[52:53], v[52:53], v[208:209] op_sel_hi:[1,0]
	v_pk_mul_f32 v[46:47], v[46:47], v[210:211] op_sel_hi:[1,0]
	v_pk_mul_f32 v[48:49], v[48:49], v[210:211] op_sel_hi:[1,0]
	v_pk_mul_f32 v[42:43], v[42:43], v[210:211] op_sel_hi:[1,0]
	v_pk_mul_f32 v[44:45], v[44:45], v[210:211] op_sel_hi:[1,0]
	v_pk_mul_f32 v[38:39], v[38:39], v[210:211] op_sel_hi:[1,0]
	v_pk_mul_f32 v[40:41], v[40:41], v[210:211] op_sel_hi:[1,0]
	v_pk_mul_f32 v[34:35], v[34:35], v[210:211] op_sel_hi:[1,0]
	v_pk_mul_f32 v[36:37], v[36:37], v[210:211] op_sel_hi:[1,0]
	v_pk_mul_f32 v[30:31], v[30:31], v[212:213] op_sel_hi:[1,0]
	v_pk_mul_f32 v[32:33], v[32:33], v[212:213] op_sel_hi:[1,0]
	v_pk_mul_f32 v[26:27], v[26:27], v[212:213] op_sel_hi:[1,0]
	v_pk_mul_f32 v[28:29], v[28:29], v[212:213] op_sel_hi:[1,0]
	v_pk_mul_f32 v[22:23], v[22:23], v[212:213] op_sel_hi:[1,0]
	v_pk_mul_f32 v[24:25], v[24:25], v[212:213] op_sel_hi:[1,0]
	v_pk_mul_f32 v[18:19], v[18:19], v[212:213] op_sel_hi:[1,0]
	v_pk_mul_f32 v[20:21], v[20:21], v[212:213] op_sel_hi:[1,0]
	v_pk_mul_f32 v[14:15], v[14:15], v[214:215] op_sel_hi:[1,0]
	v_pk_mul_f32 v[16:17], v[16:17], v[214:215] op_sel_hi:[1,0]
	v_pk_mul_f32 v[10:11], v[10:11], v[214:215] op_sel_hi:[1,0]
	v_pk_mul_f32 v[12:13], v[12:13], v[214:215] op_sel_hi:[1,0]
	v_pk_mul_f32 v[6:7], v[6:7], v[214:215] op_sel_hi:[1,0]
	v_pk_mul_f32 v[8:9], v[8:9], v[214:215] op_sel_hi:[1,0]
	v_pk_mul_f32 v[2:3], v[2:3], v[214:215] op_sel_hi:[1,0]
	v_pk_mul_f32 v[4:5], v[4:5], v[214:215] op_sel_hi:[1,0]
	v_lshl_add_u32 v150, s27, 8, v158
	v_max_f32_e32 v126, v126, v126
	v_max_f32_e32 v122, v122, v122
	v_max_f32_e32 v127, v127, v127
	v_max_f32_e32 v123, v123, v123
	v_max_f32_e32 v128, v128, v128
	v_max_f32_e32 v129, v129, v129
	v_lshl_or_b32 v152, s26, 8, v160
	v_ashrrev_i32_e32 v151, 31, v150
	v_max_f32_e32 v126, 0, v126
	v_max_f32_e32 v122, 0, v122
	v_max_f32_e32 v127, 0, v127
	v_max_f32_e32 v123, 0, v123
	v_max_f32_e32 v128, 0, v128
	v_max_f32_e32 v124, v124, v124
	v_max_f32_e32 v129, 0, v129
	v_max_f32_e32 v125, v125, v125
	v_lshlrev_b64 v[154:155], 13, v[150:151]
	v_pk_mul_f32 v[126:127], v[126:127], v[126:127]
	v_pk_mul_f32 v[122:123], v[122:123], v[122:123]
	v_max_f32_e32 v124, 0, v124
	v_max_f32_e32 v125, 0, v125
	v_pk_mul_f32 v[128:129], v[128:129], v[128:129]
	v_ashrrev_i32_e32 v153, 31, v152
	v_pk_mul_f32 v[156:157], v[124:125], v[124:125]
	v_cvt_pk_bf16_f32 v124, v126, v127
	v_cvt_pk_bf16_f32 v125, v128, v129
	v_cvt_pk_bf16_f32 v126, v122, v123
	v_lshl_add_u64 v[122:123], v[140:141], 0, v[154:155]
	v_lshlrev_b64 v[128:129], 1, v[152:153]
	v_max_f32_e32 v114, v114, v114
	v_max_f32_e32 v115, v115, v115
	v_cvt_pk_bf16_f32 v127, v156, v157
	v_lshl_add_u64 v[122:123], v[122:123], 0, v[128:129]
	v_max_f32_e32 v114, 0, v114
	v_max_f32_e32 v115, 0, v115
	global_store_dwordx4 v[122:123], v[124:127], off
	v_max_f32_e32 v118, v118, v118
	v_max_f32_e32 v119, v119, v119
	v_pk_mul_f32 v[124:125], v[114:115], v[114:115]
	v_max_f32_e32 v115, v116, v116
	v_max_f32_e32 v114, v120, v120
	v_max_f32_e32 v116, 0, v115
	v_max_f32_e32 v115, v121, v121
	v_max_f32_e32 v117, v117, v117
	v_max_f32_e32 v118, 0, v118
	v_max_f32_e32 v119, 0, v119
	v_max_f32_e32 v114, 0, v114
	v_max_f32_e32 v115, 0, v115
	v_max_f32_e32 v117, 0, v117
	v_pk_mul_f32 v[118:119], v[118:119], v[118:119]
	v_pk_mul_f32 v[120:121], v[114:115], v[114:115]
	v_pk_mul_f32 v[126:127], v[116:117], v[116:117]
	v_max_f32_e32 v106, v106, v106
	v_max_f32_e32 v107, v107, v107
	v_cvt_pk_bf16_f32 v114, v118, v119
	v_cvt_pk_bf16_f32 v115, v120, v121
	v_cvt_pk_bf16_f32 v116, v124, v125
	v_cvt_pk_bf16_f32 v117, v126, v127
	v_max_f32_e32 v106, 0, v106
	v_max_f32_e32 v107, 0, v107
	global_store_dwordx4 v[122:123], v[114:117], off offset:256
	v_max_f32_e32 v110, v110, v110
	v_max_f32_e32 v111, v111, v111
	v_or_b32_e32 v114, 16, v150
	v_pk_mul_f32 v[116:117], v[106:107], v[106:107]
	v_max_f32_e32 v107, v108, v108
	v_ashrrev_i32_e32 v115, 31, v114
	v_max_f32_e32 v110, 0, v110
	v_max_f32_e32 v111, 0, v111
	v_max_f32_e32 v106, v112, v112
	v_max_f32_e32 v108, 0, v107
	v_max_f32_e32 v107, v113, v113
	v_max_f32_e32 v109, v109, v109
	v_lshlrev_b64 v[114:115], 13, v[114:115]
	v_pk_mul_f32 v[110:111], v[110:111], v[110:111]
	v_max_f32_e32 v106, 0, v106
	v_max_f32_e32 v107, 0, v107
	v_max_f32_e32 v109, 0, v109
	v_pk_mul_f32 v[112:113], v[106:107], v[106:107]
	v_pk_mul_f32 v[118:119], v[108:109], v[108:109]
	v_cvt_pk_bf16_f32 v106, v110, v111
	v_lshl_add_u64 v[110:111], v[140:141], 0, v[114:115]
	v_max_f32_e32 v98, v98, v98
	v_max_f32_e32 v99, v99, v99
	v_cvt_pk_bf16_f32 v107, v112, v113
	v_cvt_pk_bf16_f32 v108, v116, v117
	v_cvt_pk_bf16_f32 v109, v118, v119
	v_lshl_add_u64 v[110:111], v[110:111], 0, v[128:129]
	v_max_f32_e32 v98, 0, v98
	v_max_f32_e32 v99, 0, v99
	global_store_dwordx4 v[110:111], v[106:109], off
	v_max_f32_e32 v102, v102, v102
	v_max_f32_e32 v103, v103, v103
	v_pk_mul_f32 v[106:107], v[98:99], v[98:99]
	v_max_f32_e32 v99, v100, v100
	v_max_f32_e32 v98, v104, v104
	v_max_f32_e32 v100, 0, v99
	v_max_f32_e32 v99, v105, v105
	v_max_f32_e32 v101, v101, v101
	v_max_f32_e32 v102, 0, v102
	v_max_f32_e32 v103, 0, v103
	v_max_f32_e32 v98, 0, v98
	v_max_f32_e32 v99, 0, v99
	v_max_f32_e32 v101, 0, v101
	v_pk_mul_f32 v[102:103], v[102:103], v[102:103]
	v_pk_mul_f32 v[104:105], v[98:99], v[98:99]
	v_pk_mul_f32 v[108:109], v[100:101], v[100:101]
	v_max_f32_e32 v90, v90, v90
	v_max_f32_e32 v91, v91, v91
	v_cvt_pk_bf16_f32 v98, v102, v103
	v_cvt_pk_bf16_f32 v99, v104, v105
	v_cvt_pk_bf16_f32 v100, v106, v107
	v_cvt_pk_bf16_f32 v101, v108, v109
	v_max_f32_e32 v90, 0, v90
	v_max_f32_e32 v91, 0, v91
	global_store_dwordx4 v[110:111], v[98:101], off offset:256
	v_max_f32_e32 v94, v94, v94
	v_max_f32_e32 v95, v95, v95
	v_or_b32_e32 v98, 32, v150
	v_pk_mul_f32 v[100:101], v[90:91], v[90:91]
	v_max_f32_e32 v91, v92, v92
	v_ashrrev_i32_e32 v99, 31, v98
	v_max_f32_e32 v94, 0, v94
	v_max_f32_e32 v95, 0, v95
	v_max_f32_e32 v90, v96, v96
	v_max_f32_e32 v92, 0, v91
	v_max_f32_e32 v91, v97, v97
	v_max_f32_e32 v93, v93, v93
	v_lshlrev_b64 v[98:99], 13, v[98:99]
	v_pk_mul_f32 v[94:95], v[94:95], v[94:95]
	v_max_f32_e32 v90, 0, v90
	v_max_f32_e32 v91, 0, v91
	v_max_f32_e32 v93, 0, v93
	v_pk_mul_f32 v[96:97], v[90:91], v[90:91]
	v_pk_mul_f32 v[102:103], v[92:93], v[92:93]
	v_cvt_pk_bf16_f32 v90, v94, v95
	v_lshl_add_u64 v[94:95], v[140:141], 0, v[98:99]
	v_max_f32_e32 v82, v82, v82
	v_max_f32_e32 v83, v83, v83
	v_cvt_pk_bf16_f32 v91, v96, v97
	v_cvt_pk_bf16_f32 v92, v100, v101
	v_cvt_pk_bf16_f32 v93, v102, v103
	v_lshl_add_u64 v[94:95], v[94:95], 0, v[128:129]
	v_max_f32_e32 v82, 0, v82
	v_max_f32_e32 v83, 0, v83
	global_store_dwordx4 v[94:95], v[90:93], off
	v_max_f32_e32 v86, v86, v86
	v_max_f32_e32 v87, v87, v87
	v_pk_mul_f32 v[90:91], v[82:83], v[82:83]
	v_max_f32_e32 v83, v84, v84
	v_max_f32_e32 v82, v88, v88
	v_max_f32_e32 v84, 0, v83
	v_max_f32_e32 v83, v89, v89
	v_max_f32_e32 v85, v85, v85
	v_max_f32_e32 v86, 0, v86
	v_max_f32_e32 v87, 0, v87
	v_max_f32_e32 v82, 0, v82
	v_max_f32_e32 v83, 0, v83
	v_max_f32_e32 v85, 0, v85
	v_pk_mul_f32 v[86:87], v[86:87], v[86:87]
	v_pk_mul_f32 v[88:89], v[82:83], v[82:83]
	v_pk_mul_f32 v[92:93], v[84:85], v[84:85]
	v_max_f32_e32 v74, v74, v74
	v_max_f32_e32 v75, v75, v75
	v_cvt_pk_bf16_f32 v82, v86, v87
	v_cvt_pk_bf16_f32 v83, v88, v89
	v_cvt_pk_bf16_f32 v84, v90, v91
	v_cvt_pk_bf16_f32 v85, v92, v93
	v_max_f32_e32 v74, 0, v74
	v_max_f32_e32 v75, 0, v75
	global_store_dwordx4 v[94:95], v[82:85], off offset:256
	v_max_f32_e32 v78, v78, v78
	v_max_f32_e32 v79, v79, v79
	v_or_b32_e32 v82, 48, v150
	v_pk_mul_f32 v[84:85], v[74:75], v[74:75]
	v_max_f32_e32 v75, v76, v76
	v_ashrrev_i32_e32 v83, 31, v82
	v_max_f32_e32 v78, 0, v78
	v_max_f32_e32 v79, 0, v79
	v_max_f32_e32 v74, v80, v80
	v_max_f32_e32 v76, 0, v75
	v_max_f32_e32 v75, v81, v81
	v_max_f32_e32 v77, v77, v77
	v_lshlrev_b64 v[82:83], 13, v[82:83]
	v_pk_mul_f32 v[78:79], v[78:79], v[78:79]
	v_max_f32_e32 v74, 0, v74
	v_max_f32_e32 v75, 0, v75
	v_max_f32_e32 v77, 0, v77
	v_pk_mul_f32 v[80:81], v[74:75], v[74:75]
	v_pk_mul_f32 v[86:87], v[76:77], v[76:77]
	v_cvt_pk_bf16_f32 v74, v78, v79
	v_lshl_add_u64 v[78:79], v[140:141], 0, v[82:83]
	v_max_f32_e32 v66, v66, v66
	v_max_f32_e32 v67, v67, v67
	v_cvt_pk_bf16_f32 v75, v80, v81
	v_cvt_pk_bf16_f32 v76, v84, v85
	v_cvt_pk_bf16_f32 v77, v86, v87
	v_lshl_add_u64 v[78:79], v[78:79], 0, v[128:129]
	v_max_f32_e32 v66, 0, v66
	v_max_f32_e32 v67, 0, v67
	global_store_dwordx4 v[78:79], v[74:77], off
	v_max_f32_e32 v70, v70, v70
	v_max_f32_e32 v71, v71, v71
	v_pk_mul_f32 v[74:75], v[66:67], v[66:67]
	v_max_f32_e32 v67, v68, v68
	v_max_f32_e32 v66, v72, v72
	v_max_f32_e32 v68, 0, v67
	v_max_f32_e32 v67, v73, v73
	v_max_f32_e32 v69, v69, v69
	v_max_f32_e32 v70, 0, v70
	v_max_f32_e32 v71, 0, v71
	v_max_f32_e32 v66, 0, v66
	v_max_f32_e32 v67, 0, v67
	v_max_f32_e32 v69, 0, v69
	v_pk_mul_f32 v[70:71], v[70:71], v[70:71]
	v_pk_mul_f32 v[72:73], v[66:67], v[66:67]
	v_pk_mul_f32 v[76:77], v[68:69], v[68:69]
	v_max_f32_e32 v58, v58, v58
	v_max_f32_e32 v59, v59, v59
	v_cvt_pk_bf16_f32 v66, v70, v71
	v_cvt_pk_bf16_f32 v67, v72, v73
	v_cvt_pk_bf16_f32 v68, v74, v75
	v_cvt_pk_bf16_f32 v69, v76, v77
	v_max_f32_e32 v58, 0, v58
	v_max_f32_e32 v59, 0, v59
	global_store_dwordx4 v[78:79], v[66:69], off offset:256
	v_max_f32_e32 v62, v62, v62
	v_max_f32_e32 v63, v63, v63
	v_pk_mul_f32 v[66:67], v[58:59], v[58:59]
	v_max_f32_e32 v59, v60, v60
	v_max_f32_e32 v58, v64, v64
	v_max_f32_e32 v60, 0, v59
	v_max_f32_e32 v59, v65, v65
	v_max_f32_e32 v58, 0, v58
	v_max_f32_e32 v59, 0, v59
	v_max_f32_e32 v61, v61, v61
	v_max_f32_e32 v62, 0, v62
	v_max_f32_e32 v63, 0, v63
	v_max_f32_e32 v61, 0, v61
	v_pk_mul_f32 v[64:65], v[58:59], v[58:59]
	v_pk_mul_f32 v[62:63], v[62:63], v[62:63]
	v_pk_mul_f32 v[68:69], v[60:61], v[60:61]
	v_cvt_pk_bf16_f32 v59, v64, v65
	v_add_co_u32_e32 v64, vcc, s31, v122
	v_max_f32_e32 v50, v50, v50
	v_max_f32_e32 v51, v51, v51
	v_cvt_pk_bf16_f32 v58, v62, v63
	v_cvt_pk_bf16_f32 v60, v66, v67
	v_cvt_pk_bf16_f32 v61, v68, v69
	v_addc_co_u32_e32 v65, vcc, 0, v123, vcc
	v_max_f32_e32 v50, 0, v50
	v_max_f32_e32 v51, 0, v51
	global_store_dwordx4 v[64:65], v[58:61], off
	v_max_f32_e32 v54, v54, v54
	v_max_f32_e32 v55, v55, v55
	v_pk_mul_f32 v[58:59], v[50:51], v[50:51]
	v_max_f32_e32 v51, v52, v52
	v_max_f32_e32 v50, v56, v56
	v_max_f32_e32 v52, 0, v51
	v_max_f32_e32 v51, v57, v57
	v_max_f32_e32 v53, v53, v53
	v_max_f32_e32 v54, 0, v54
	v_max_f32_e32 v55, 0, v55
	v_max_f32_e32 v50, 0, v50
	v_max_f32_e32 v51, 0, v51
	v_max_f32_e32 v53, 0, v53
	v_pk_mul_f32 v[54:55], v[54:55], v[54:55]
	v_pk_mul_f32 v[56:57], v[50:51], v[50:51]
	v_pk_mul_f32 v[60:61], v[52:53], v[52:53]
	v_max_f32_e32 v42, v42, v42
	v_max_f32_e32 v43, v43, v43
	v_lshl_add_u64 v[62:63], v[122:123], 0, s[72:73]
	v_cvt_pk_bf16_f32 v50, v54, v55
	v_cvt_pk_bf16_f32 v51, v56, v57
	v_cvt_pk_bf16_f32 v52, v58, v59
	v_cvt_pk_bf16_f32 v53, v60, v61
	v_max_f32_e32 v42, 0, v42
	v_max_f32_e32 v43, 0, v43
	global_store_dwordx4 v[62:63], v[50:53], off offset:256
	v_max_f32_e32 v46, v46, v46
	v_max_f32_e32 v47, v47, v47
	v_pk_mul_f32 v[50:51], v[42:43], v[42:43]
	v_max_f32_e32 v43, v44, v44
	v_max_f32_e32 v42, v48, v48
	v_max_f32_e32 v44, 0, v43
	v_max_f32_e32 v43, v49, v49
	v_max_f32_e32 v42, 0, v42
	v_max_f32_e32 v43, 0, v43
	v_max_f32_e32 v45, v45, v45
	v_max_f32_e32 v46, 0, v46
	v_max_f32_e32 v47, 0, v47
	v_max_f32_e32 v45, 0, v45
	v_pk_mul_f32 v[48:49], v[42:43], v[42:43]
	s_mov_b32 s13, 0x120000
	v_pk_mul_f32 v[46:47], v[46:47], v[46:47]
	v_pk_mul_f32 v[52:53], v[44:45], v[44:45]
	v_cvt_pk_bf16_f32 v43, v48, v49
	v_add_co_u32_e32 v48, vcc, s13, v122
	v_max_f32_e32 v34, v34, v34
	v_max_f32_e32 v35, v35, v35
	v_cvt_pk_bf16_f32 v42, v46, v47
	v_cvt_pk_bf16_f32 v44, v50, v51
	v_cvt_pk_bf16_f32 v45, v52, v53
	v_addc_co_u32_e32 v49, vcc, 0, v123, vcc
	v_max_f32_e32 v34, 0, v34
	v_max_f32_e32 v35, 0, v35
	global_store_dwordx4 v[48:49], v[42:45], off
	v_max_f32_e32 v38, v38, v38
	v_max_f32_e32 v39, v39, v39
	v_pk_mul_f32 v[42:43], v[34:35], v[34:35]
	v_max_f32_e32 v35, v36, v36
	v_max_f32_e32 v34, v40, v40
	v_max_f32_e32 v36, 0, v35
	v_max_f32_e32 v35, v41, v41
	v_max_f32_e32 v37, v37, v37
	v_max_f32_e32 v38, 0, v38
	v_max_f32_e32 v39, 0, v39
	v_max_f32_e32 v34, 0, v34
	v_max_f32_e32 v35, 0, v35
	v_max_f32_e32 v37, 0, v37
	s_mov_b64 s[16:17], 0x120000
	v_pk_mul_f32 v[38:39], v[38:39], v[38:39]
	v_pk_mul_f32 v[40:41], v[34:35], v[34:35]
	v_pk_mul_f32 v[44:45], v[36:37], v[36:37]
	v_max_f32_e32 v26, v26, v26
	v_max_f32_e32 v27, v27, v27
	v_lshl_add_u64 v[46:47], v[122:123], 0, s[16:17]
	v_cvt_pk_bf16_f32 v34, v38, v39
	v_cvt_pk_bf16_f32 v35, v40, v41
	v_cvt_pk_bf16_f32 v36, v42, v43
	v_cvt_pk_bf16_f32 v37, v44, v45
	v_max_f32_e32 v26, 0, v26
	v_max_f32_e32 v27, 0, v27
	global_store_dwordx4 v[46:47], v[34:37], off offset:256
	v_max_f32_e32 v30, v30, v30
	v_max_f32_e32 v31, v31, v31
	v_pk_mul_f32 v[34:35], v[26:27], v[26:27]
	v_max_f32_e32 v27, v28, v28
	v_max_f32_e32 v26, v32, v32
	v_max_f32_e32 v28, 0, v27
	v_max_f32_e32 v27, v33, v33
	v_max_f32_e32 v26, 0, v26
	v_max_f32_e32 v27, 0, v27
	v_max_f32_e32 v29, v29, v29
	v_max_f32_e32 v30, 0, v30
	v_max_f32_e32 v31, 0, v31
	v_max_f32_e32 v29, 0, v29
	v_pk_mul_f32 v[32:33], v[26:27], v[26:27]
	s_mov_b32 s13, 0x140000
	v_pk_mul_f32 v[30:31], v[30:31], v[30:31]
	v_pk_mul_f32 v[36:37], v[28:29], v[28:29]
	v_cvt_pk_bf16_f32 v27, v32, v33
	v_add_co_u32_e32 v32, vcc, s13, v122
	v_max_f32_e32 v18, v18, v18
	v_max_f32_e32 v19, v19, v19
	v_cvt_pk_bf16_f32 v26, v30, v31
	v_cvt_pk_bf16_f32 v28, v34, v35
	v_cvt_pk_bf16_f32 v29, v36, v37
	v_addc_co_u32_e32 v33, vcc, 0, v123, vcc
	v_max_f32_e32 v18, 0, v18
	v_max_f32_e32 v19, 0, v19
	global_store_dwordx4 v[32:33], v[26:29], off
	v_max_f32_e32 v22, v22, v22
	v_max_f32_e32 v23, v23, v23
	v_pk_mul_f32 v[26:27], v[18:19], v[18:19]
	v_max_f32_e32 v19, v20, v20
	v_max_f32_e32 v18, v24, v24
	v_max_f32_e32 v20, 0, v19
	v_max_f32_e32 v19, v25, v25
	v_max_f32_e32 v21, v21, v21
	v_max_f32_e32 v22, 0, v22
	v_max_f32_e32 v23, 0, v23
	v_max_f32_e32 v18, 0, v18
	v_max_f32_e32 v19, 0, v19
	v_max_f32_e32 v21, 0, v21
	s_mov_b64 s[16:17], 0x140000
	v_pk_mul_f32 v[22:23], v[22:23], v[22:23]
	v_pk_mul_f32 v[24:25], v[18:19], v[18:19]
	v_pk_mul_f32 v[28:29], v[20:21], v[20:21]
	v_max_f32_e32 v10, v10, v10
	v_max_f32_e32 v11, v11, v11
	v_lshl_add_u64 v[30:31], v[122:123], 0, s[16:17]
	v_cvt_pk_bf16_f32 v18, v22, v23
	v_cvt_pk_bf16_f32 v19, v24, v25
	v_cvt_pk_bf16_f32 v20, v26, v27
	v_cvt_pk_bf16_f32 v21, v28, v29
	v_max_f32_e32 v10, 0, v10
	v_max_f32_e32 v11, 0, v11
	global_store_dwordx4 v[30:31], v[18:21], off offset:256
	v_max_f32_e32 v14, v14, v14
	v_max_f32_e32 v15, v15, v15
	v_pk_mul_f32 v[18:19], v[10:11], v[10:11]
	v_max_f32_e32 v11, v12, v12
	v_max_f32_e32 v10, v16, v16
	v_max_f32_e32 v12, 0, v11
	v_max_f32_e32 v11, v17, v17
	v_max_f32_e32 v10, 0, v10
	v_max_f32_e32 v11, 0, v11
	v_max_f32_e32 v13, v13, v13
	v_max_f32_e32 v14, 0, v14
	v_max_f32_e32 v15, 0, v15
	v_max_f32_e32 v13, 0, v13
	v_pk_mul_f32 v[16:17], v[10:11], v[10:11]
	s_mov_b32 s13, 0x160000
	v_pk_mul_f32 v[14:15], v[14:15], v[14:15]
	v_pk_mul_f32 v[20:21], v[12:13], v[12:13]
	v_cvt_pk_bf16_f32 v11, v16, v17
	v_add_co_u32_e32 v16, vcc, s13, v122
	v_max_f32_e32 v2, v2, v2
	v_max_f32_e32 v3, v3, v3
	v_cvt_pk_bf16_f32 v10, v14, v15
	v_cvt_pk_bf16_f32 v12, v18, v19
	v_cvt_pk_bf16_f32 v13, v20, v21
	v_addc_co_u32_e32 v17, vcc, 0, v123, vcc
	v_max_f32_e32 v2, 0, v2
	v_max_f32_e32 v3, 0, v3
	global_store_dwordx4 v[16:17], v[10:13], off
	v_max_f32_e32 v6, v6, v6
	v_max_f32_e32 v7, v7, v7
	v_pk_mul_f32 v[10:11], v[2:3], v[2:3]
	v_max_f32_e32 v3, v4, v4
	v_max_f32_e32 v2, v8, v8
	v_max_f32_e32 v4, 0, v3
	v_max_f32_e32 v3, v9, v9
	v_max_f32_e32 v5, v5, v5
	v_max_f32_e32 v6, 0, v6
	v_max_f32_e32 v7, 0, v7
	v_max_f32_e32 v2, 0, v2
	v_max_f32_e32 v3, 0, v3
	v_max_f32_e32 v5, 0, v5
	s_mov_b64 s[16:17], 0x160000
	v_pk_mul_f32 v[6:7], v[6:7], v[6:7]
	v_pk_mul_f32 v[8:9], v[2:3], v[2:3]
	v_pk_mul_f32 v[12:13], v[4:5], v[4:5]
	v_lshl_add_u64 v[14:15], v[122:123], 0, s[16:17]
	v_cvt_pk_bf16_f32 v2, v6, v7
	v_cvt_pk_bf16_f32 v3, v8, v9
	v_cvt_pk_bf16_f32 v4, v10, v11
	v_cvt_pk_bf16_f32 v5, v12, v13
	s_andn2_b64 vcc, exec, s[4:5]
	s_mov_b64 s[4:5], -1
	global_store_dwordx4 v[14:15], v[2:5], off offset:256
	s_cbranch_vccnz .LBB0_999
	s_andn2_b64 vcc, exec, s[6:7]
	s_cbranch_vccnz .LBB0_998
	s_barrier
	s_branch .LBB0_998
